# GU: wr==0 alignment barrier moved ~100 instructions into the epilogue (overlaps other half's last MFMA segment)
# speedup vs baseline: 1.0063x; 1.0063x over previous
.LBB0_1446:
	s_add_u32 s16, s4, 0xfffc0080
	s_addc_u32 s17, s5, -1
	s_add_i32 s42, 0, 0x10000
	s_cmp_eq_u32 s41, 12
	s_cselect_b32 s19, s11, s17
	s_cselect_b32 s18, s37, s16
	s_cselect_b32 s17, s9, s40
	s_cselect_b32 s16, s38, s39
	s_add_i32 s44, 0, 0x14000
	v_add_u32_e32 v142, s42, v195
	v_add_u32_e32 v162, s44, v195
	ds_read_b128 v[130:133], v142
	ds_read_b128 v[134:137], v142 offset:1024
	ds_read_b128 v[138:141], v142 offset:2048
	ds_read_b128 v[142:145], v142 offset:3072
	ds_read_b128 v[146:149], v162
	ds_read_b128 v[150:153], v162 offset:1024
	ds_read_b128 v[174:177], v162 offset:2048
	ds_read_b128 v[178:181], v162 offset:3072
	v_lshl_add_u64 v[162:163], s[4:5], 0, v[170:171]
	s_add_i32 m0, s23, 0xc000
	ds_read_b128 v[182:185], v199
	ds_read_b128 v[186:189], v199 offset:1024
	ds_read_b128 v[200:203], v199 offset:2048
	ds_read_b128 v[204:207], v199 offset:3072
	ds_read_b128 v[220:223], v199 offset:4096
	ds_read_b128 v[224:227], v199 offset:5120
	ds_read_b128 v[228:231], v199 offset:6144
	ds_read_b128 v[232:235], v199 offset:7168
	global_load_lds_dwordx4 v[162:163], off
	v_lshl_add_u64 v[162:163], s[4:5], 0, v[172:173]
	s_add_i32 m0, s23, 0xe000
	s_nop 0
	global_load_lds_dwordx4 v[162:163], off
	s_waitcnt vmcnt(8)
	s_waitcnt lgkmcnt(0)
	s_barrier
	s_setprio 1
	s_waitcnt lgkmcnt(0)
	v_mfma_f32_16x16x32_bf16 v[126:129], v[130:133], v[182:185], v[126:129]
	v_mfma_f32_16x16x32_bf16 v[118:121], v[138:141], v[182:185], v[118:121]
	v_mfma_f32_16x16x32_bf16 v[110:113], v[130:133], v[200:203], v[110:113]
	v_mfma_f32_16x16x32_bf16 v[102:105], v[138:141], v[200:203], v[102:105]
	v_mfma_f32_16x16x32_bf16 v[94:97], v[130:133], v[220:223], v[94:97]
	v_mfma_f32_16x16x32_bf16 v[86:89], v[138:141], v[220:223], v[86:89]
	v_mfma_f32_16x16x32_bf16 v[78:81], v[130:133], v[228:231], v[78:81]
	v_mfma_f32_16x16x32_bf16 v[70:73], v[138:141], v[228:231], v[70:73]
	v_mfma_f32_16x16x32_bf16 v[126:129], v[134:137], v[186:189], v[126:129]
	v_mfma_f32_16x16x32_bf16 v[118:121], v[142:145], v[186:189], v[118:121]
	v_mfma_f32_16x16x32_bf16 v[110:113], v[134:137], v[204:207], v[110:113]
	v_mfma_f32_16x16x32_bf16 v[102:105], v[142:145], v[204:207], v[102:105]
	v_mfma_f32_16x16x32_bf16 v[94:97], v[134:137], v[224:227], v[94:97]
	v_mfma_f32_16x16x32_bf16 v[86:89], v[142:145], v[224:227], v[86:89]
	v_mfma_f32_16x16x32_bf16 v[78:81], v[134:137], v[232:235], v[78:81]
	v_mfma_f32_16x16x32_bf16 v[70:73], v[142:145], v[232:235], v[70:73]
	s_setprio 0
	s_setprio 1
	v_mfma_f32_16x16x32_bf16 v[122:125], v[146:149], v[182:185], v[122:125]
	v_mfma_f32_16x16x32_bf16 v[114:117], v[174:177], v[182:185], v[114:117]
	v_mfma_f32_16x16x32_bf16 v[106:109], v[146:149], v[200:203], v[106:109]
	v_mfma_f32_16x16x32_bf16 v[98:101], v[174:177], v[200:203], v[98:101]
	v_mfma_f32_16x16x32_bf16 v[90:93], v[146:149], v[220:223], v[90:93]
	v_mfma_f32_16x16x32_bf16 v[82:85], v[174:177], v[220:223], v[82:85]
	v_mfma_f32_16x16x32_bf16 v[74:77], v[146:149], v[228:231], v[74:77]
	v_mfma_f32_16x16x32_bf16 v[66:69], v[174:177], v[228:231], v[66:69]
	v_mfma_f32_16x16x32_bf16 v[122:125], v[150:153], v[186:189], v[122:125]
	v_mfma_f32_16x16x32_bf16 v[114:117], v[178:181], v[186:189], v[114:117]
	v_mfma_f32_16x16x32_bf16 v[106:109], v[150:153], v[204:207], v[106:109]
	v_mfma_f32_16x16x32_bf16 v[98:101], v[178:181], v[204:207], v[98:101]
	v_mfma_f32_16x16x32_bf16 v[90:93], v[150:153], v[224:227], v[90:93]
	v_mfma_f32_16x16x32_bf16 v[82:85], v[178:181], v[224:227], v[82:85]
	v_mfma_f32_16x16x32_bf16 v[74:77], v[150:153], v[232:235], v[74:77]
	v_mfma_f32_16x16x32_bf16 v[66:69], v[178:181], v[232:235], v[66:69]
	s_setprio 0
	s_barrier
	s_add_i32 s42, s42, s22
	v_lshl_add_u64 v[162:163], s[16:17], 0, v[0:1]
	s_mov_b32 m0, s42
	ds_read_b128 v[182:185], v199 offset:16384
	ds_read_b128 v[186:189], v199 offset:17408
	ds_read_b128 v[200:203], v199 offset:18432
	ds_read_b128 v[204:207], v199 offset:19456
	ds_read_b128 v[220:223], v199 offset:20480
	ds_read_b128 v[224:227], v199 offset:21504
	ds_read_b128 v[228:231], v199 offset:22528
	ds_read_b128 v[232:235], v199 offset:23552
	global_load_lds_dwordx4 v[162:163], off
	s_add_i32 m0, s42, 0x2000
	s_add_u32 s42, s16, 0x40000
	v_lshl_add_u64 v[190:191], s[16:17], 0, v[154:155]
	s_addc_u32 s43, s17, 0
	s_add_i32 s44, s44, s22
	global_load_lds_dwordx4 v[190:191], off
	v_lshl_add_u64 v[196:197], s[42:43], 0, v[0:1]
	s_mov_b32 m0, s44
	v_lshl_add_u64 v[208:209], s[18:19], 0, v[156:157]
	global_load_lds_dwordx4 v[196:197], off
	v_lshl_add_u64 v[196:197], s[42:43], 0, v[154:155]
	s_add_i32 m0, s44, 0x2000
	s_nop 0
	global_load_lds_dwordx4 v[196:197], off
	v_lshl_add_u64 v[196:197], s[18:19], 0, v[158:159]
	s_mov_b32 m0, s23
	s_nop 0
	global_load_lds_dwordx4 v[196:197], off
	s_mov_b32 m0, s26
	s_nop 0
	global_load_lds_dwordx4 v[208:209], off
	s_waitcnt vmcnt(8)
	s_waitcnt lgkmcnt(0)
	s_barrier
	s_setprio 1
	s_waitcnt lgkmcnt(0)
	v_mfma_f32_16x16x32_bf16 v[62:65], v[130:133], v[182:185], v[62:65]
	v_mfma_f32_16x16x32_bf16 v[54:57], v[138:141], v[182:185], v[54:57]
	v_mfma_f32_16x16x32_bf16 v[46:49], v[130:133], v[200:203], v[46:49]
	v_mfma_f32_16x16x32_bf16 v[38:41], v[138:141], v[200:203], v[38:41]
	v_mfma_f32_16x16x32_bf16 v[30:33], v[130:133], v[220:223], v[30:33]
	v_mfma_f32_16x16x32_bf16 v[22:25], v[138:141], v[220:223], v[22:25]
	v_mfma_f32_16x16x32_bf16 v[14:17], v[130:133], v[228:231], v[14:17]
	v_mfma_f32_16x16x32_bf16 v[6:9], v[138:141], v[228:231], v[6:9]
	v_mfma_f32_16x16x32_bf16 v[62:65], v[134:137], v[186:189], v[62:65]
	v_mfma_f32_16x16x32_bf16 v[54:57], v[142:145], v[186:189], v[54:57]
	v_mfma_f32_16x16x32_bf16 v[46:49], v[134:137], v[204:207], v[46:49]
	v_mfma_f32_16x16x32_bf16 v[38:41], v[142:145], v[204:207], v[38:41]
	v_mfma_f32_16x16x32_bf16 v[30:33], v[134:137], v[224:227], v[30:33]
	v_mfma_f32_16x16x32_bf16 v[22:25], v[142:145], v[224:227], v[22:25]
	v_mfma_f32_16x16x32_bf16 v[14:17], v[134:137], v[232:235], v[14:17]
	v_mfma_f32_16x16x32_bf16 v[6:9], v[142:145], v[232:235], v[6:9]
	s_setprio 0
	s_setprio 1
	v_mfma_f32_16x16x32_bf16 v[58:61], v[146:149], v[182:185], v[58:61]
	v_mfma_f32_16x16x32_bf16 v[50:53], v[174:177], v[182:185], v[50:53]
	v_mfma_f32_16x16x32_bf16 v[42:45], v[146:149], v[200:203], v[42:45]
	v_mfma_f32_16x16x32_bf16 v[34:37], v[174:177], v[200:203], v[34:37]
	v_mfma_f32_16x16x32_bf16 v[26:29], v[146:149], v[220:223], v[26:29]
	v_mfma_f32_16x16x32_bf16 v[18:21], v[174:177], v[220:223], v[18:21]
	v_mfma_f32_16x16x32_bf16 v[10:13], v[146:149], v[228:231], v[10:13]
	v_mfma_f32_16x16x32_bf16 v[2:5], v[174:177], v[228:231], v[2:5]
	v_mfma_f32_16x16x32_bf16 v[58:61], v[150:153], v[186:189], v[58:61]
	v_mfma_f32_16x16x32_bf16 v[50:53], v[178:181], v[186:189], v[50:53]
	v_mfma_f32_16x16x32_bf16 v[42:45], v[150:153], v[204:207], v[42:45]
	v_mfma_f32_16x16x32_bf16 v[34:37], v[178:181], v[204:207], v[34:37]
	v_mfma_f32_16x16x32_bf16 v[26:29], v[150:153], v[224:227], v[26:29]
	v_mfma_f32_16x16x32_bf16 v[18:21], v[178:181], v[224:227], v[18:21]
	v_mfma_f32_16x16x32_bf16 v[10:13], v[150:153], v[232:235], v[10:13]
	v_mfma_f32_16x16x32_bf16 v[2:5], v[178:181], v[232:235], v[2:5]
	s_setprio 0
	s_barrier
	s_add_i32 s42, 0, 0x18000
	s_add_i32 s43, 0, 0x1c000
	v_add_u32_e32 v142, s42, v195
	v_add_u32_e32 v164, s43, v195
	ds_read_b128 v[130:133], v142
	ds_read_b128 v[134:137], v142 offset:1024
	ds_read_b128 v[138:141], v142 offset:2048
	ds_read_b128 v[142:145], v142 offset:3072
	ds_read_b128 v[146:149], v164
	ds_read_b128 v[150:153], v164 offset:1024
	ds_read_b128 v[174:177], v164 offset:2048
	ds_read_b128 v[178:181], v164 offset:3072
	s_add_u32 s18, s18, 0x40000
	s_addc_u32 s19, s19, 0
	s_mov_b32 m0, s27
	v_lshl_add_u64 v[214:215], s[18:19], 0, v[158:159]
	ds_read_b128 v[182:185], v199 offset:32768
	ds_read_b128 v[186:189], v199 offset:33792
	ds_read_b128 v[200:203], v199 offset:34816
	ds_read_b128 v[204:207], v199 offset:35840
	ds_read_b128 v[220:223], v199 offset:36864
	ds_read_b128 v[224:227], v199 offset:37888
	ds_read_b128 v[228:231], v199 offset:38912
	ds_read_b128 v[232:235], v199 offset:39936
	global_load_lds_dwordx4 v[214:215], off
	v_lshl_add_u64 v[214:215], s[18:19], 0, v[156:157]
	s_mov_b32 m0, s28
	s_nop 0
	global_load_lds_dwordx4 v[214:215], off
	s_waitcnt vmcnt(8)
	s_waitcnt lgkmcnt(0)
	s_barrier
	s_setprio 1
	s_waitcnt lgkmcnt(0)
	v_mfma_f32_16x16x32_bf16 v[126:129], v[130:133], v[182:185], v[126:129]
	v_mfma_f32_16x16x32_bf16 v[118:121], v[138:141], v[182:185], v[118:121]
	v_mfma_f32_16x16x32_bf16 v[110:113], v[130:133], v[200:203], v[110:113]
	v_mfma_f32_16x16x32_bf16 v[102:105], v[138:141], v[200:203], v[102:105]
	v_mfma_f32_16x16x32_bf16 v[94:97], v[130:133], v[220:223], v[94:97]
	v_mfma_f32_16x16x32_bf16 v[86:89], v[138:141], v[220:223], v[86:89]
	v_mfma_f32_16x16x32_bf16 v[78:81], v[130:133], v[228:231], v[78:81]
	v_mfma_f32_16x16x32_bf16 v[70:73], v[138:141], v[228:231], v[70:73]
	v_mfma_f32_16x16x32_bf16 v[126:129], v[134:137], v[186:189], v[126:129]
	v_mfma_f32_16x16x32_bf16 v[118:121], v[142:145], v[186:189], v[118:121]
	v_mfma_f32_16x16x32_bf16 v[110:113], v[134:137], v[204:207], v[110:113]
	v_mfma_f32_16x16x32_bf16 v[102:105], v[142:145], v[204:207], v[102:105]
	v_mfma_f32_16x16x32_bf16 v[94:97], v[134:137], v[224:227], v[94:97]
	v_mfma_f32_16x16x32_bf16 v[86:89], v[142:145], v[224:227], v[86:89]
	v_mfma_f32_16x16x32_bf16 v[78:81], v[134:137], v[232:235], v[78:81]
	v_mfma_f32_16x16x32_bf16 v[70:73], v[142:145], v[232:235], v[70:73]
	s_setprio 0
	s_setprio 1
	v_mfma_f32_16x16x32_bf16 v[122:125], v[146:149], v[182:185], v[122:125]
	v_mfma_f32_16x16x32_bf16 v[114:117], v[174:177], v[182:185], v[114:117]
	v_mfma_f32_16x16x32_bf16 v[106:109], v[146:149], v[200:203], v[106:109]
	v_mfma_f32_16x16x32_bf16 v[98:101], v[174:177], v[200:203], v[98:101]
	v_mfma_f32_16x16x32_bf16 v[90:93], v[146:149], v[220:223], v[90:93]
	v_mfma_f32_16x16x32_bf16 v[82:85], v[174:177], v[220:223], v[82:85]
	v_mfma_f32_16x16x32_bf16 v[74:77], v[146:149], v[228:231], v[74:77]
	v_mfma_f32_16x16x32_bf16 v[66:69], v[174:177], v[228:231], v[66:69]
	v_mfma_f32_16x16x32_bf16 v[122:125], v[150:153], v[186:189], v[122:125]
	v_mfma_f32_16x16x32_bf16 v[114:117], v[178:181], v[186:189], v[114:117]
	v_mfma_f32_16x16x32_bf16 v[106:109], v[150:153], v[204:207], v[106:109]
	v_mfma_f32_16x16x32_bf16 v[98:101], v[178:181], v[204:207], v[98:101]
	v_mfma_f32_16x16x32_bf16 v[90:93], v[150:153], v[224:227], v[90:93]
	v_mfma_f32_16x16x32_bf16 v[82:85], v[178:181], v[224:227], v[82:85]
	v_mfma_f32_16x16x32_bf16 v[74:77], v[150:153], v[232:235], v[74:77]
	v_mfma_f32_16x16x32_bf16 v[66:69], v[178:181], v[232:235], v[66:69]
	s_setprio 0
	s_barrier
	s_add_i32 s18, s42, s22
	v_lshl_add_u64 v[162:163], v[162:163], 0, s[86:87]
	s_mov_b32 m0, s18
	ds_read_b128 v[182:185], v199 offset:49152
	ds_read_b128 v[186:189], v199 offset:50176
	ds_read_b128 v[200:203], v199 offset:51200
	ds_read_b128 v[204:207], v199 offset:52224
	ds_read_b128 v[220:223], v199 offset:53248
	ds_read_b128 v[224:227], v199 offset:54272
	ds_read_b128 v[228:231], v199 offset:55296
	ds_read_b128 v[232:235], v199 offset:56320
	global_load_lds_dwordx4 v[162:163], off
	s_add_i32 m0, s18, 0x2000
	s_add_u32 s16, s16, 0x40080
	v_lshl_add_u64 v[162:163], v[190:191], 0, s[86:87]
	s_addc_u32 s17, s17, 0
	s_add_i32 s18, s43, s22
	global_load_lds_dwordx4 v[162:163], off
	v_lshl_add_u64 v[162:163], s[16:17], 0, v[0:1]
	s_mov_b32 m0, s18
	s_nop 0
	global_load_lds_dwordx4 v[162:163], off
	v_lshl_add_u64 v[162:163], s[16:17], 0, v[154:155]
	s_add_i32 m0, s18, 0x2000
	s_nop 0
	global_load_lds_dwordx4 v[162:163], off
	v_lshl_add_u64 v[162:163], v[196:197], 0, s[86:87]
	s_mov_b32 m0, s29
	s_nop 0
	global_load_lds_dwordx4 v[162:163], off
	v_lshl_add_u64 v[162:163], v[208:209], 0, s[86:87]
	s_mov_b32 m0, s30
	s_nop 0
	global_load_lds_dwordx4 v[162:163], off
	s_waitcnt vmcnt(8)
	s_waitcnt lgkmcnt(0)
	s_barrier
	s_setprio 1
	s_waitcnt lgkmcnt(0)
	v_mfma_f32_16x16x32_bf16 v[62:65], v[130:133], v[182:185], v[62:65]
	v_mfma_f32_16x16x32_bf16 v[54:57], v[138:141], v[182:185], v[54:57]
	v_mfma_f32_16x16x32_bf16 v[46:49], v[130:133], v[200:203], v[46:49]
	v_mfma_f32_16x16x32_bf16 v[38:41], v[138:141], v[200:203], v[38:41]
	v_mfma_f32_16x16x32_bf16 v[30:33], v[130:133], v[220:223], v[30:33]
	v_mfma_f32_16x16x32_bf16 v[22:25], v[138:141], v[220:223], v[22:25]
	v_mfma_f32_16x16x32_bf16 v[14:17], v[130:133], v[228:231], v[14:17]
	v_mfma_f32_16x16x32_bf16 v[6:9], v[138:141], v[228:231], v[6:9]
	v_mfma_f32_16x16x32_bf16 v[62:65], v[134:137], v[186:189], v[62:65]
	v_mfma_f32_16x16x32_bf16 v[54:57], v[142:145], v[186:189], v[54:57]
	v_mfma_f32_16x16x32_bf16 v[46:49], v[134:137], v[204:207], v[46:49]
	v_mfma_f32_16x16x32_bf16 v[38:41], v[142:145], v[204:207], v[38:41]
	v_mfma_f32_16x16x32_bf16 v[30:33], v[134:137], v[224:227], v[30:33]
	v_mfma_f32_16x16x32_bf16 v[22:25], v[142:145], v[224:227], v[22:25]
	v_mfma_f32_16x16x32_bf16 v[14:17], v[134:137], v[232:235], v[14:17]
	v_mfma_f32_16x16x32_bf16 v[6:9], v[142:145], v[232:235], v[6:9]
	s_setprio 0
	s_setprio 1
	v_mfma_f32_16x16x32_bf16 v[58:61], v[146:149], v[182:185], v[58:61]
	v_mfma_f32_16x16x32_bf16 v[50:53], v[174:177], v[182:185], v[50:53]
	v_mfma_f32_16x16x32_bf16 v[42:45], v[146:149], v[200:203], v[42:45]
	v_mfma_f32_16x16x32_bf16 v[34:37], v[174:177], v[200:203], v[34:37]
	v_mfma_f32_16x16x32_bf16 v[26:29], v[146:149], v[220:223], v[26:29]
	v_mfma_f32_16x16x32_bf16 v[18:21], v[174:177], v[220:223], v[18:21]
	v_mfma_f32_16x16x32_bf16 v[10:13], v[146:149], v[228:231], v[10:13]
	v_mfma_f32_16x16x32_bf16 v[2:5], v[174:177], v[228:231], v[2:5]
	v_mfma_f32_16x16x32_bf16 v[58:61], v[150:153], v[186:189], v[58:61]
	v_mfma_f32_16x16x32_bf16 v[50:53], v[178:181], v[186:189], v[50:53]
	v_mfma_f32_16x16x32_bf16 v[42:45], v[150:153], v[204:207], v[42:45]
	v_mfma_f32_16x16x32_bf16 v[34:37], v[178:181], v[204:207], v[34:37]
	v_mfma_f32_16x16x32_bf16 v[26:29], v[150:153], v[224:227], v[26:29]
	v_mfma_f32_16x16x32_bf16 v[18:21], v[178:181], v[224:227], v[18:21]
	v_mfma_f32_16x16x32_bf16 v[10:13], v[150:153], v[232:235], v[10:13]
	v_mfma_f32_16x16x32_bf16 v[2:5], v[178:181], v[232:235], v[2:5]
	s_setprio 0
	s_barrier
	s_add_i32 s41, s41, 2
	s_add_u32 s4, s4, 0x100
	s_addc_u32 s5, s5, 0
	s_add_u32 s39, s39, 0x100
	s_addc_u32 s40, s40, 0
	s_cmp_gt_u32 s41, 13
	s_cbranch_scc0 .LBB0_1446
.LBB0_1449:
	s_cmp_eq_u32 s101, s36
	s_cbranch_scc1 .Lgu_rs_cached
	v_lshl_add_u32 v188, s36, 8, v193
	v_ashrrev_i32_e32 v189, 31, v188
	v_lshlrev_b64 v[130:131], 6, v[188:189]
	v_or_b32_e32 v186, 16, v188
	v_lshl_add_u64 v[130:131], v[160:161], 0, v[130:131]
	v_ashrrev_i32_e32 v187, 31, v186
	global_load_dwordx4 v[200:203], v[130:131], off
	v_lshlrev_b64 v[130:131], 6, v[186:187]
	v_lshl_add_u64 v[130:131], v[160:161], 0, v[130:131]
	global_load_dwordx4 v[204:207], v[130:131], off
	v_or_b32_e32 v184, 32, v188
	v_ashrrev_i32_e32 v185, 31, v184
	v_lshlrev_b64 v[130:131], 6, v[184:185]
	v_or_b32_e32 v182, 48, v188
	v_lshl_add_u64 v[130:131], v[160:161], 0, v[130:131]
	v_ashrrev_i32_e32 v183, 31, v182
	global_load_dwordx4 v[150:153], v[130:131], off
	v_lshlrev_b64 v[130:131], 6, v[182:183]
	v_lshl_add_u64 v[130:131], v[160:161], 0, v[130:131]
	global_load_dwordx4 v[146:149], v[130:131], off
	v_add_u32_e32 v180, 0x80, v188
	v_ashrrev_i32_e32 v181, 31, v180
	v_lshlrev_b64 v[130:131], 6, v[180:181]
	v_add_u32_e32 v178, 0x90, v188
	v_lshl_add_u64 v[130:131], v[160:161], 0, v[130:131]
	v_ashrrev_i32_e32 v179, 31, v178
	global_load_dwordx4 v[142:145], v[130:131], off
	v_lshlrev_b64 v[130:131], 6, v[178:179]
	v_lshl_add_u64 v[130:131], v[160:161], 0, v[130:131]
	global_load_dwordx4 v[138:141], v[130:131], off
	v_add_u32_e32 v176, 0xa0, v188
	v_ashrrev_i32_e32 v177, 31, v176
	v_lshlrev_b64 v[130:131], 6, v[176:177]
	v_add_u32_e32 v174, 0xb0, v188
	v_lshl_add_u64 v[130:131], v[160:161], 0, v[130:131]
	v_ashrrev_i32_e32 v175, 31, v174
	global_load_dwordx4 v[134:137], v[130:131], off
	v_lshlrev_b64 v[130:131], 6, v[174:175]
	v_lshl_add_u64 v[130:131], v[160:161], 0, v[130:131]
	global_load_dwordx4 v[130:133], v[130:131], off
	v_and_b32_e32 v163, 64, v211
	v_xor_b32_e32 v162, 16, v211
	v_add_u32_e32 v163, 64, v163
	v_cmp_lt_i32_e32 vcc, v162, v163
	s_mov_b32 s4, 0x358637bd
	s_mov_b32 s16, 0x3a800000
	v_cndmask_b32_e32 v162, v211, v162, vcc
	v_lshlrev_b32_e32 v177, 2, v162
	v_xor_b32_e32 v162, 32, v211
	v_cmp_lt_i32_e32 vcc, v162, v163
	v_lshl_or_b32 v190, s35, 7, v198
	v_ashrrev_i32_e32 v191, 31, v190
	v_cndmask_b32_e32 v162, v211, v162, vcc
	v_lshlrev_b32_e32 v175, 2, v162
	s_movk_i32 s9, 0x1600
	s_waitcnt vmcnt(0)
	v_mov_b32_e32 v162, v201
	v_mov_b32_e32 v163, v202
	v_mov_b32_e32 v201, v203
	v_mov_b32_e32 v196, v205
	v_mov_b32_e32 v197, v206
	v_mov_b32_e32 v205, v207
	v_pk_add_f32 v[162:163], v[162:163], v[200:201]
	v_pk_add_f32 v[196:197], v[196:197], v[204:205]
	v_mov_b32_e32 v201, v162
	v_mov_b32_e32 v200, v196
	v_mov_b32_e32 v162, v197
	v_pk_add_f32 v[162:163], v[200:201], v[162:163]
	ds_bpermute_b32 v197, v177, v163
	ds_bpermute_b32 v196, v177, v162
	s_waitcnt lgkmcnt(0)
	v_pk_add_f32 v[162:163], v[162:163], v[196:197]
	ds_bpermute_b32 v197, v175, v163
	ds_bpermute_b32 v196, v175, v162
	s_waitcnt lgkmcnt(0)
	v_pk_add_f32 v[162:163], v[162:163], v[196:197]
	v_mov_b64_e32 v[196:197], s[4:5]
	v_pk_fma_f32 v[162:163], v[162:163], s[16:17], v[196:197] op_sel_hi:[1,0,0]
	s_nop 0
	v_mul_f32_e32 v164, 0x4b800000, v163
	v_cmp_gt_f32_e64 s[4:5], s91, v163
	v_cmp_gt_f32_e32 vcc, s91, v162
	s_nop 0
	v_cndmask_b32_e64 v163, v163, v164, s[4:5]
	v_rsq_f32_e32 v163, v163
	s_nop 0
	v_mul_f32_e32 v164, 0x45800000, v163
	v_cndmask_b32_e64 v194, v163, v164, s[4:5]
	v_mul_f32_e32 v163, 0x4b800000, v162
	v_cndmask_b32_e32 v162, v162, v163, vcc
	v_rsq_f32_e32 v162, v162
	s_nop 0
	s_nop 0
	s_nop 0
	v_mul_f32_e32 v163, 0x45800000, v162
	v_cndmask_b32_e32 v192, v162, v163, vcc
	v_mov_b32_e32 v162, v151
	v_mov_b32_e32 v163, v152
	v_mov_b32_e32 v151, v153
	v_mov_b32_e32 v152, v147
	v_mov_b32_e32 v153, v148
	v_mov_b32_e32 v147, v149
	v_pk_add_f32 v[150:151], v[162:163], v[150:151]
	v_pk_add_f32 v[146:147], v[152:153], v[146:147]
	v_mov_b32_e32 v149, v150
	v_mov_b32_e32 v148, v146
	v_mov_b32_e32 v150, v147
	v_pk_add_f32 v[146:147], v[148:149], v[150:151]
	ds_bpermute_b32 v149, v177, v147
	ds_bpermute_b32 v148, v177, v146
	v_mov_b32_e32 v150, v143
	v_mov_b32_e32 v151, v144
	v_mov_b32_e32 v143, v145
	v_mov_b32_e32 v144, v139
	v_mov_b32_e32 v145, v140
	v_mov_b32_e32 v139, v141
	v_pk_add_f32 v[142:143], v[150:151], v[142:143]
	v_pk_add_f32 v[138:139], v[144:145], v[138:139]
	s_waitcnt lgkmcnt(0)
	v_pk_add_f32 v[146:147], v[146:147], v[148:149]
	v_mov_b32_e32 v140, v138
	v_mov_b32_e32 v141, v142
	v_mov_b32_e32 v142, v139
	ds_bpermute_b32 v149, v175, v147
	ds_bpermute_b32 v148, v175, v146
	v_pk_add_f32 v[138:139], v[140:141], v[142:143]
	ds_bpermute_b32 v141, v177, v139
	ds_bpermute_b32 v140, v177, v138
	v_mov_b32_e32 v142, v135
	v_mov_b32_e32 v143, v136
	v_mov_b32_e32 v135, v137
	v_mov_b32_e32 v136, v131
	v_mov_b32_e32 v137, v132
	v_mov_b32_e32 v131, v133
	s_waitcnt lgkmcnt(2)
	v_pk_add_f32 v[146:147], v[146:147], v[148:149]
	v_pk_add_f32 v[134:135], v[142:143], v[134:135]
	v_pk_add_f32 v[130:131], v[136:137], v[130:131]
	v_pk_fma_f32 v[146:147], v[146:147], s[16:17], v[196:197] op_sel_hi:[1,0,0]
	s_waitcnt lgkmcnt(0)
	v_pk_add_f32 v[138:139], v[138:139], v[140:141]
	v_mov_b32_e32 v132, v130
	v_mov_b32_e32 v133, v134
	v_mov_b32_e32 v134, v131
	v_mul_f32_e32 v148, 0x4b800000, v147
	v_cmp_gt_f32_e64 s[4:5], s91, v147
	ds_bpermute_b32 v141, v175, v139
	ds_bpermute_b32 v140, v175, v138
	v_pk_add_f32 v[130:131], v[132:133], v[134:135]
	v_cndmask_b32_e64 v147, v147, v148, s[4:5]
	ds_bpermute_b32 v133, v177, v131
	ds_bpermute_b32 v132, v177, v130
	v_rsq_f32_e32 v147, v147
	s_waitcnt lgkmcnt(2)
	v_pk_add_f32 v[138:139], v[138:139], v[140:141]
	v_cmp_gt_f32_e32 vcc, s91, v146
	v_pk_fma_f32 v[138:139], v[138:139], s[16:17], v[196:197] op_sel_hi:[1,0,0]
	v_mul_f32_e32 v148, 0x45800000, v147
	s_waitcnt lgkmcnt(0)
	v_pk_add_f32 v[130:131], v[130:131], v[132:133]
	v_cndmask_b32_e64 v148, v147, v148, s[4:5]
	v_mul_f32_e32 v147, 0x4b800000, v146
	v_mul_f32_e32 v140, 0x4b800000, v139
	v_cmp_gt_f32_e64 s[4:5], s91, v139
	ds_bpermute_b32 v133, v175, v131
	ds_bpermute_b32 v132, v175, v130
	v_cndmask_b32_e32 v146, v146, v147, vcc
	v_cndmask_b32_e64 v139, v139, v140, s[4:5]
	v_rsq_f32_e32 v146, v146
	v_rsq_f32_e32 v139, v139
	s_waitcnt lgkmcnt(0)
	v_pk_add_f32 v[130:131], v[130:131], v[132:133]
	s_nop 0
	v_mul_f32_e32 v147, 0x45800000, v146
	v_mul_f32_e32 v140, 0x45800000, v139
	v_pk_fma_f32 v[130:131], v[130:131], s[16:17], v[196:197] op_sel_hi:[1,0,0]
	v_cndmask_b32_e32 v146, v146, v147, vcc
	v_cmp_gt_f32_e32 vcc, s91, v138
	v_cndmask_b32_e64 v140, v139, v140, s[4:5]
	v_mul_f32_e32 v139, 0x4b800000, v138
	v_mul_f32_e32 v132, 0x4b800000, v131
	v_cmp_gt_f32_e64 s[4:5], s91, v131
	v_cndmask_b32_e32 v138, v138, v139, vcc
	v_rsq_f32_e32 v138, v138
	v_cndmask_b32_e64 v131, v131, v132, s[4:5]
	v_rsq_f32_e32 v131, v131
	s_nop 0
	v_mul_f32_e32 v139, 0x45800000, v138
	v_cndmask_b32_e32 v138, v138, v139, vcc
	v_mul_f32_e32 v132, 0x45800000, v131
	v_cmp_gt_f32_e32 vcc, s91, v130
	v_cndmask_b32_e64 v132, v131, v132, s[4:5]
	v_mul_f32_e32 v131, 0x4b800000, v130
	v_cndmask_b32_e32 v130, v130, v131, vcc
	v_rsq_f32_e32 v130, v130
	s_nop 0
	s_nop 0
	s_nop 0
	v_mul_f32_e32 v131, 0x45800000, v130
	v_cndmask_b32_e32 v130, v130, v131, vcc
	v_mov_b32_e32 v236, v194
	v_mov_b32_e32 v237, v192
	v_mov_b32_e32 v238, v148
	v_mov_b32_e32 v239, v146
	v_mov_b32_e32 v248, v140
	v_mov_b32_e32 v249, v138
	v_mov_b32_e32 v250, v132
	v_mov_b32_e32 v251, v130
	s_mov_b32 s101, s36
	s_branch .Lgu_rs_done

.Lgu_rs_done:
	v_readlane_b32 s4, v254, 32
	v_readlane_b32 s5, v254, 33
	v_pk_mul_f32 v[126:127], v[126:127], v[194:195] op_sel_hi:[1,0]
	v_pk_mul_f32 v[122:123], v[122:123], v[194:195] op_sel_hi:[1,0]
	v_pk_mul_f32 v[124:125], v[124:125], v[194:195] op_sel_hi:[1,0]
	v_pk_mul_f32 v[118:119], v[118:119], v[194:195] op_sel_hi:[1,0]
	v_pk_mul_f32 v[114:115], v[114:115], v[194:195] op_sel_hi:[1,0]
	v_pk_mul_f32 v[116:117], v[116:117], v[194:195] op_sel_hi:[1,0]
	v_mul_f32_e32 v131, 0xbfb8aa3b, v126
	v_exp_f32_e32 v131, v131
	v_pk_mul_f32 v[110:111], v[110:111], v[192:193] op_sel_hi:[1,0]
	v_pk_mul_f32 v[106:107], v[106:107], v[192:193] op_sel_hi:[1,0]
	v_pk_mul_f32 v[108:109], v[108:109], v[192:193] op_sel_hi:[1,0]
	v_add_f32_e32 v131, 1.0, v131
	v_rcp_f32_e32 v134, v131
	v_mul_f32_e32 v131, 0xbfb8aa3b, v127
	v_exp_f32_e32 v131, v131
	v_pk_mul_f32 v[102:103], v[102:103], v[192:193] op_sel_hi:[1,0]
	v_pk_mul_f32 v[98:99], v[98:99], v[192:193] op_sel_hi:[1,0]
	v_pk_mul_f32 v[100:101], v[100:101], v[192:193] op_sel_hi:[1,0]
	v_add_f32_e32 v131, 1.0, v131
	v_rcp_f32_e32 v135, v131
	v_pk_mul_f32 v[94:95], v[94:95], v[148:149] op_sel_hi:[1,0]
	v_pk_mul_f32 v[90:91], v[90:91], v[148:149] op_sel_hi:[1,0]
	v_pk_mul_f32 v[92:93], v[92:93], v[148:149] op_sel_hi:[1,0]
	v_pk_mul_f32 v[126:127], v[126:127], v[134:135]
	v_pk_mul_f32 v[86:87], v[86:87], v[148:149] op_sel_hi:[1,0]
	v_pk_mul_f32 v[122:123], v[122:123], v[126:127]
	v_pk_mul_f32 v[126:127], v[128:129], v[194:195] op_sel_hi:[1,0]
	v_pk_mul_f32 v[82:83], v[82:83], v[148:149] op_sel_hi:[1,0]
	v_mul_f32_e32 v128, 0xbfb8aa3b, v126
	v_mul_f32_e32 v129, 0xbfb8aa3b, v127
	v_exp_f32_e32 v128, v128
	v_exp_f32_e32 v129, v129
	v_pk_mul_f32 v[84:85], v[84:85], v[148:149] op_sel_hi:[1,0]
	v_pk_mul_f32 v[78:79], v[78:79], v[146:147] op_sel_hi:[1,0]
	v_add_f32_e32 v128, 1.0, v128
	v_add_f32_e32 v129, 1.0, v129
	v_rcp_f32_e32 v128, v128
	v_rcp_f32_e32 v129, v129
	v_pk_mul_f32 v[74:75], v[74:75], v[146:147] op_sel_hi:[1,0]
	v_pk_mul_f32 v[76:77], v[76:77], v[146:147] op_sel_hi:[1,0]
	v_pk_mul_f32 v[70:71], v[70:71], v[146:147] op_sel_hi:[1,0]
	v_pk_mul_f32 v[126:127], v[126:127], v[128:129]
	v_pk_mul_f32 v[66:67], v[66:67], v[146:147] op_sel_hi:[1,0]
	v_pk_mul_f32 v[124:125], v[124:125], v[126:127]
	v_mul_f32_e32 v126, 0xbfb8aa3b, v118
	v_mul_f32_e32 v127, 0xbfb8aa3b, v119
	v_exp_f32_e32 v126, v126
	v_exp_f32_e32 v127, v127
	v_pk_mul_f32 v[68:69], v[68:69], v[146:147] op_sel_hi:[1,0]
	v_pk_mul_f32 v[62:63], v[62:63], v[140:141] op_sel_hi:[1,0]
	v_add_f32_e32 v126, 1.0, v126
	v_add_f32_e32 v127, 1.0, v127
	v_rcp_f32_e32 v126, v126
	v_rcp_f32_e32 v127, v127
	v_pk_mul_f32 v[58:59], v[58:59], v[140:141] op_sel_hi:[1,0]
	v_pk_mul_f32 v[60:61], v[60:61], v[140:141] op_sel_hi:[1,0]
	v_pk_mul_f32 v[54:55], v[54:55], v[140:141] op_sel_hi:[1,0]
	v_pk_mul_f32 v[118:119], v[118:119], v[126:127]
	v_pk_mul_f32 v[50:51], v[50:51], v[140:141] op_sel_hi:[1,0]
	v_pk_mul_f32 v[114:115], v[114:115], v[118:119]
	v_pk_mul_f32 v[118:119], v[120:121], v[194:195] op_sel_hi:[1,0]
	v_pk_mul_f32 v[52:53], v[52:53], v[140:141] op_sel_hi:[1,0]
	v_mul_f32_e32 v120, 0xbfb8aa3b, v118
	v_mul_f32_e32 v121, 0xbfb8aa3b, v119
	v_exp_f32_e32 v120, v120
	v_exp_f32_e32 v121, v121
	v_pk_mul_f32 v[46:47], v[46:47], v[138:139] op_sel_hi:[1,0]
	v_pk_mul_f32 v[42:43], v[42:43], v[138:139] op_sel_hi:[1,0]
	v_add_f32_e32 v120, 1.0, v120
	v_add_f32_e32 v121, 1.0, v121
	v_rcp_f32_e32 v120, v120
	v_rcp_f32_e32 v121, v121
	v_pk_mul_f32 v[44:45], v[44:45], v[138:139] op_sel_hi:[1,0]
	v_pk_mul_f32 v[38:39], v[38:39], v[138:139] op_sel_hi:[1,0]
	v_pk_mul_f32 v[34:35], v[34:35], v[138:139] op_sel_hi:[1,0]
	v_pk_mul_f32 v[118:119], v[118:119], v[120:121]
	v_cvt_pk_bf16_f32 v120, v114, v115
	v_pk_mul_f32 v[116:117], v[116:117], v[118:119]
	v_mov_b64_e32 v[114:115], s[4:5]
	v_cvt_pk_bf16_f32 v118, v122, v123
	v_cvt_pk_bf16_f32 v121, v116, v117
	v_mad_i64_i32 v[122:123], s[4:5], v188, s9, v[114:115]
	v_lshlrev_b64 v[116:117], 1, v[190:191]
	v_cvt_pk_bf16_f32 v119, v124, v125
	v_lshl_add_u64 v[122:123], v[122:123], 0, v[116:117]
	global_store_dwordx4 v[122:123], v[118:121], off
	s_cmp_lg_u64 s[6:7], 0
	s_cbranch_scc0 .Lgu_nox0
	s_barrier
.Lgu_nox0:
	v_pk_mul_f32 v[36:37], v[36:37], v[138:139] op_sel_hi:[1,0]
	v_pk_mul_f32 v[30:31], v[30:31], v[132:133] op_sel_hi:[1,0]
	v_mul_f32_e32 v118, 0xbfb8aa3b, v110
	v_mul_f32_e32 v119, 0xbfb8aa3b, v111
	v_exp_f32_e32 v118, v118
	v_exp_f32_e32 v119, v119
	v_pk_mul_f32 v[26:27], v[26:27], v[132:133] op_sel_hi:[1,0]
	v_pk_mul_f32 v[28:29], v[28:29], v[132:133] op_sel_hi:[1,0]
	v_add_f32_e32 v118, 1.0, v118
	v_add_f32_e32 v119, 1.0, v119
	v_rcp_f32_e32 v118, v118
	v_rcp_f32_e32 v119, v119
	v_pk_mul_f32 v[22:23], v[22:23], v[132:133] op_sel_hi:[1,0]
	v_pk_mul_f32 v[18:19], v[18:19], v[132:133] op_sel_hi:[1,0]
	v_pk_mul_f32 v[20:21], v[20:21], v[132:133] op_sel_hi:[1,0]
	v_pk_mul_f32 v[110:111], v[110:111], v[118:119]
	v_pk_mul_f32 v[14:15], v[14:15], v[130:131] op_sel_hi:[1,0]
	v_pk_mul_f32 v[106:107], v[106:107], v[110:111]
	v_pk_mul_f32 v[110:111], v[112:113], v[192:193] op_sel_hi:[1,0]
	v_pk_mul_f32 v[10:11], v[10:11], v[130:131] op_sel_hi:[1,0]
	v_mul_f32_e32 v112, 0xbfb8aa3b, v110
	v_mul_f32_e32 v113, 0xbfb8aa3b, v111
	v_exp_f32_e32 v112, v112
	v_exp_f32_e32 v113, v113
	v_pk_mul_f32 v[12:13], v[12:13], v[130:131] op_sel_hi:[1,0]
	v_pk_mul_f32 v[6:7], v[6:7], v[130:131] op_sel_hi:[1,0]
	v_add_f32_e32 v112, 1.0, v112
	v_add_f32_e32 v113, 1.0, v113
	v_rcp_f32_e32 v112, v112
	v_rcp_f32_e32 v113, v113
	v_pk_mul_f32 v[2:3], v[2:3], v[130:131] op_sel_hi:[1,0]
	v_pk_mul_f32 v[4:5], v[4:5], v[130:131] op_sel_hi:[1,0]
	s_andn2_b64 vcc, exec, s[0:1]
	v_pk_mul_f32 v[110:111], v[110:111], v[112:113]
	s_nop 0
	v_pk_mul_f32 v[108:109], v[108:109], v[110:111]
	v_mul_f32_e32 v110, 0xbfb8aa3b, v102
	v_mul_f32_e32 v111, 0xbfb8aa3b, v103
	v_exp_f32_e32 v110, v110
	v_exp_f32_e32 v111, v111
	v_add_f32_e32 v110, 1.0, v110
	v_add_f32_e32 v111, 1.0, v111
	v_rcp_f32_e32 v110, v110
	v_rcp_f32_e32 v111, v111
	s_nop 0
	v_pk_mul_f32 v[102:103], v[102:103], v[110:111]
	s_nop 0
	v_pk_mul_f32 v[102:103], v[98:99], v[102:103]
	v_pk_mul_f32 v[98:99], v[104:105], v[192:193] op_sel_hi:[1,0]
	s_nop 0
	v_mul_f32_e32 v104, 0xbfb8aa3b, v98
	v_mul_f32_e32 v105, 0xbfb8aa3b, v99
	v_exp_f32_e32 v104, v104
	v_exp_f32_e32 v105, v105
	v_add_f32_e32 v104, 1.0, v104
	v_add_f32_e32 v105, 1.0, v105
	v_rcp_f32_e32 v104, v104
	v_rcp_f32_e32 v105, v105
	s_nop 0
	v_pk_mul_f32 v[98:99], v[98:99], v[104:105]
	s_nop 0
	v_pk_mul_f32 v[104:105], v[100:101], v[98:99]
	v_cvt_pk_bf16_f32 v100, v102, v103
	v_mad_i64_i32 v[102:103], s[4:5], v186, s9, v[114:115]
	v_cvt_pk_bf16_f32 v98, v106, v107
	v_cvt_pk_bf16_f32 v99, v108, v109
	v_cvt_pk_bf16_f32 v101, v104, v105
	v_lshl_add_u64 v[102:103], v[102:103], 0, v[116:117]
	global_store_dwordx4 v[102:103], v[98:101], off
	s_nop 1
	v_mul_f32_e32 v98, 0xbfb8aa3b, v94
	v_mul_f32_e32 v99, 0xbfb8aa3b, v95
	v_exp_f32_e32 v98, v98
	v_exp_f32_e32 v99, v99
	v_add_f32_e32 v98, 1.0, v98
	v_add_f32_e32 v99, 1.0, v99
	v_rcp_f32_e32 v98, v98
	v_rcp_f32_e32 v99, v99
	s_nop 0
	v_pk_mul_f32 v[94:95], v[94:95], v[98:99]
	s_nop 0
	v_pk_mul_f32 v[90:91], v[90:91], v[94:95]
	v_pk_mul_f32 v[94:95], v[96:97], v[148:149] op_sel_hi:[1,0]
	s_nop 0
	v_mul_f32_e32 v96, 0xbfb8aa3b, v94
	v_mul_f32_e32 v97, 0xbfb8aa3b, v95
	v_exp_f32_e32 v96, v96
	v_exp_f32_e32 v97, v97
	v_add_f32_e32 v96, 1.0, v96
	v_add_f32_e32 v97, 1.0, v97
	v_rcp_f32_e32 v96, v96
	v_rcp_f32_e32 v97, v97
	s_nop 0
	v_pk_mul_f32 v[94:95], v[94:95], v[96:97]
	s_nop 0
	v_pk_mul_f32 v[92:93], v[92:93], v[94:95]
	v_mul_f32_e32 v94, 0xbfb8aa3b, v86
	v_mul_f32_e32 v95, 0xbfb8aa3b, v87
	v_exp_f32_e32 v94, v94
	v_exp_f32_e32 v95, v95
	v_add_f32_e32 v94, 1.0, v94
	v_add_f32_e32 v95, 1.0, v95
	v_rcp_f32_e32 v94, v94
	v_rcp_f32_e32 v95, v95
	s_nop 0
	v_pk_mul_f32 v[86:87], v[86:87], v[94:95]
	s_nop 0
	v_pk_mul_f32 v[86:87], v[82:83], v[86:87]
	v_pk_mul_f32 v[82:83], v[88:89], v[148:149] op_sel_hi:[1,0]
	s_nop 0
	v_mul_f32_e32 v88, 0xbfb8aa3b, v82
	v_mul_f32_e32 v89, 0xbfb8aa3b, v83
	v_exp_f32_e32 v88, v88
	v_exp_f32_e32 v89, v89
	v_add_f32_e32 v88, 1.0, v88
	v_add_f32_e32 v89, 1.0, v89
	v_rcp_f32_e32 v88, v88
	v_rcp_f32_e32 v89, v89
	s_nop 0
	v_pk_mul_f32 v[82:83], v[82:83], v[88:89]
	s_nop 0
	v_pk_mul_f32 v[88:89], v[84:85], v[82:83]
	v_cvt_pk_bf16_f32 v84, v86, v87
	v_mad_i64_i32 v[86:87], s[4:5], v184, s9, v[114:115]
	v_cvt_pk_bf16_f32 v82, v90, v91
	v_cvt_pk_bf16_f32 v83, v92, v93
	v_cvt_pk_bf16_f32 v85, v88, v89
	v_lshl_add_u64 v[86:87], v[86:87], 0, v[116:117]
	global_store_dwordx4 v[86:87], v[82:85], off
	s_nop 1
	v_mul_f32_e32 v82, 0xbfb8aa3b, v78
	v_mul_f32_e32 v83, 0xbfb8aa3b, v79
	v_exp_f32_e32 v82, v82
	v_exp_f32_e32 v83, v83
	v_add_f32_e32 v82, 1.0, v82
	v_add_f32_e32 v83, 1.0, v83
	v_rcp_f32_e32 v82, v82
	v_rcp_f32_e32 v83, v83
	s_nop 0
	v_pk_mul_f32 v[78:79], v[78:79], v[82:83]
	s_nop 0
	v_pk_mul_f32 v[74:75], v[74:75], v[78:79]
	v_pk_mul_f32 v[78:79], v[80:81], v[146:147] op_sel_hi:[1,0]
	s_nop 0
	v_mul_f32_e32 v80, 0xbfb8aa3b, v78
	v_mul_f32_e32 v81, 0xbfb8aa3b, v79
	v_exp_f32_e32 v80, v80
	v_exp_f32_e32 v81, v81
	v_add_f32_e32 v80, 1.0, v80
	v_add_f32_e32 v81, 1.0, v81
	v_rcp_f32_e32 v80, v80
	v_rcp_f32_e32 v81, v81
	s_nop 0
	v_pk_mul_f32 v[78:79], v[78:79], v[80:81]
	s_nop 0
	v_pk_mul_f32 v[76:77], v[76:77], v[78:79]
	v_mul_f32_e32 v78, 0xbfb8aa3b, v70
	v_mul_f32_e32 v79, 0xbfb8aa3b, v71
	v_exp_f32_e32 v78, v78
	v_exp_f32_e32 v79, v79
	v_add_f32_e32 v78, 1.0, v78
	v_add_f32_e32 v79, 1.0, v79
	v_rcp_f32_e32 v78, v78
	v_rcp_f32_e32 v79, v79
	s_nop 0
	v_pk_mul_f32 v[70:71], v[70:71], v[78:79]
	s_nop 0
	v_pk_mul_f32 v[70:71], v[66:67], v[70:71]
	v_pk_mul_f32 v[66:67], v[72:73], v[146:147] op_sel_hi:[1,0]
	s_nop 0
	v_mul_f32_e32 v72, 0xbfb8aa3b, v66
	v_mul_f32_e32 v73, 0xbfb8aa3b, v67
	v_exp_f32_e32 v72, v72
	v_exp_f32_e32 v73, v73
	v_add_f32_e32 v72, 1.0, v72
	v_add_f32_e32 v73, 1.0, v73
	v_rcp_f32_e32 v72, v72
	v_rcp_f32_e32 v73, v73
	s_nop 0
	v_pk_mul_f32 v[66:67], v[66:67], v[72:73]
	s_nop 0
	v_pk_mul_f32 v[72:73], v[68:69], v[66:67]
	v_cvt_pk_bf16_f32 v68, v70, v71
	v_mad_i64_i32 v[70:71], s[4:5], v182, s9, v[114:115]
	v_cvt_pk_bf16_f32 v66, v74, v75
	v_cvt_pk_bf16_f32 v67, v76, v77
	v_cvt_pk_bf16_f32 v69, v72, v73
	v_lshl_add_u64 v[70:71], v[70:71], 0, v[116:117]
	global_store_dwordx4 v[70:71], v[66:69], off
	s_nop 1
	v_mul_f32_e32 v66, 0xbfb8aa3b, v62
	v_mul_f32_e32 v67, 0xbfb8aa3b, v63
	v_exp_f32_e32 v66, v66
	v_exp_f32_e32 v67, v67
	v_add_f32_e32 v66, 1.0, v66
	v_add_f32_e32 v67, 1.0, v67
	v_rcp_f32_e32 v66, v66
	v_rcp_f32_e32 v67, v67
	s_nop 0
	v_pk_mul_f32 v[62:63], v[62:63], v[66:67]
	s_nop 0
	v_pk_mul_f32 v[58:59], v[58:59], v[62:63]
	v_pk_mul_f32 v[62:63], v[64:65], v[140:141] op_sel_hi:[1,0]
	s_nop 0
	v_mul_f32_e32 v64, 0xbfb8aa3b, v62
	v_mul_f32_e32 v65, 0xbfb8aa3b, v63
	v_exp_f32_e32 v64, v64
	v_exp_f32_e32 v65, v65
	v_add_f32_e32 v64, 1.0, v64
	v_add_f32_e32 v65, 1.0, v65
	v_rcp_f32_e32 v64, v64
	v_rcp_f32_e32 v65, v65
	s_nop 0
	v_pk_mul_f32 v[62:63], v[62:63], v[64:65]
	s_nop 0
	v_pk_mul_f32 v[60:61], v[60:61], v[62:63]
	v_mul_f32_e32 v62, 0xbfb8aa3b, v54
	v_mul_f32_e32 v63, 0xbfb8aa3b, v55
	v_exp_f32_e32 v62, v62
	v_exp_f32_e32 v63, v63
	v_add_f32_e32 v62, 1.0, v62
	v_add_f32_e32 v63, 1.0, v63
	v_rcp_f32_e32 v62, v62
	v_rcp_f32_e32 v63, v63
	s_nop 0
	v_pk_mul_f32 v[54:55], v[54:55], v[62:63]
	s_nop 0
	v_pk_mul_f32 v[54:55], v[50:51], v[54:55]
	v_pk_mul_f32 v[50:51], v[56:57], v[140:141] op_sel_hi:[1,0]
	s_nop 0
	v_mul_f32_e32 v56, 0xbfb8aa3b, v50
	v_mul_f32_e32 v57, 0xbfb8aa3b, v51
	v_exp_f32_e32 v56, v56
	v_exp_f32_e32 v57, v57
	v_add_f32_e32 v56, 1.0, v56
	v_add_f32_e32 v57, 1.0, v57
	v_rcp_f32_e32 v56, v56
	v_rcp_f32_e32 v57, v57
	s_nop 0
	v_pk_mul_f32 v[50:51], v[50:51], v[56:57]
	s_nop 0
	v_pk_mul_f32 v[56:57], v[52:53], v[50:51]
	v_cvt_pk_bf16_f32 v52, v54, v55
	v_mad_i64_i32 v[54:55], s[4:5], v180, s9, v[114:115]
	v_cvt_pk_bf16_f32 v50, v58, v59
	v_cvt_pk_bf16_f32 v51, v60, v61
	v_cvt_pk_bf16_f32 v53, v56, v57
	v_lshl_add_u64 v[54:55], v[54:55], 0, v[116:117]
	global_store_dwordx4 v[54:55], v[50:53], off
	s_nop 1
	v_mul_f32_e32 v50, 0xbfb8aa3b, v46
	v_mul_f32_e32 v51, 0xbfb8aa3b, v47
	v_exp_f32_e32 v50, v50
	v_exp_f32_e32 v51, v51
	v_add_f32_e32 v50, 1.0, v50
	v_add_f32_e32 v51, 1.0, v51
	v_rcp_f32_e32 v50, v50
	v_rcp_f32_e32 v51, v51
	s_nop 0
	v_pk_mul_f32 v[46:47], v[46:47], v[50:51]
	s_nop 0
	v_pk_mul_f32 v[42:43], v[42:43], v[46:47]
	v_pk_mul_f32 v[46:47], v[48:49], v[138:139] op_sel_hi:[1,0]
	s_nop 0
	v_mul_f32_e32 v48, 0xbfb8aa3b, v46
	v_mul_f32_e32 v49, 0xbfb8aa3b, v47
	v_exp_f32_e32 v48, v48
	v_exp_f32_e32 v49, v49
	v_add_f32_e32 v48, 1.0, v48
	v_add_f32_e32 v49, 1.0, v49
	v_rcp_f32_e32 v48, v48
	v_rcp_f32_e32 v49, v49
	s_nop 0
	v_pk_mul_f32 v[46:47], v[46:47], v[48:49]
	s_nop 0
	v_pk_mul_f32 v[44:45], v[44:45], v[46:47]
	v_mul_f32_e32 v46, 0xbfb8aa3b, v38
	v_mul_f32_e32 v47, 0xbfb8aa3b, v39
	v_exp_f32_e32 v46, v46
	v_exp_f32_e32 v47, v47
	v_add_f32_e32 v46, 1.0, v46
	v_add_f32_e32 v47, 1.0, v47
	v_rcp_f32_e32 v46, v46
	v_rcp_f32_e32 v47, v47
	s_nop 0
	v_pk_mul_f32 v[38:39], v[38:39], v[46:47]
	s_nop 0
	v_pk_mul_f32 v[38:39], v[34:35], v[38:39]
	v_pk_mul_f32 v[34:35], v[40:41], v[138:139] op_sel_hi:[1,0]
	s_nop 0
	v_mul_f32_e32 v40, 0xbfb8aa3b, v34
	v_mul_f32_e32 v41, 0xbfb8aa3b, v35
	v_exp_f32_e32 v40, v40
	v_exp_f32_e32 v41, v41
	v_add_f32_e32 v40, 1.0, v40
	v_add_f32_e32 v41, 1.0, v41
	v_rcp_f32_e32 v40, v40
	v_rcp_f32_e32 v41, v41
	s_nop 0
	v_pk_mul_f32 v[34:35], v[34:35], v[40:41]
	s_nop 0
	v_pk_mul_f32 v[40:41], v[36:37], v[34:35]
	v_cvt_pk_bf16_f32 v36, v38, v39
	v_mad_i64_i32 v[38:39], s[4:5], v178, s9, v[114:115]
	v_cvt_pk_bf16_f32 v34, v42, v43
	v_cvt_pk_bf16_f32 v35, v44, v45
	v_cvt_pk_bf16_f32 v37, v40, v41
	v_lshl_add_u64 v[38:39], v[38:39], 0, v[116:117]
	global_store_dwordx4 v[38:39], v[34:37], off
	s_nop 1
	v_mul_f32_e32 v34, 0xbfb8aa3b, v30
	v_mul_f32_e32 v35, 0xbfb8aa3b, v31
	v_exp_f32_e32 v34, v34
	v_exp_f32_e32 v35, v35
	v_add_f32_e32 v34, 1.0, v34
	v_add_f32_e32 v35, 1.0, v35
	v_rcp_f32_e32 v34, v34
	v_rcp_f32_e32 v35, v35
	s_nop 0
	v_pk_mul_f32 v[30:31], v[30:31], v[34:35]
	s_nop 0
	v_pk_mul_f32 v[26:27], v[26:27], v[30:31]
	v_pk_mul_f32 v[30:31], v[32:33], v[132:133] op_sel_hi:[1,0]
	s_nop 0
	v_mul_f32_e32 v32, 0xbfb8aa3b, v30
	v_mul_f32_e32 v33, 0xbfb8aa3b, v31
	v_exp_f32_e32 v32, v32
	v_exp_f32_e32 v33, v33
	v_add_f32_e32 v32, 1.0, v32
	v_add_f32_e32 v33, 1.0, v33
	v_rcp_f32_e32 v32, v32
	v_rcp_f32_e32 v33, v33
	s_nop 0
	v_pk_mul_f32 v[30:31], v[30:31], v[32:33]
	s_nop 0
	v_pk_mul_f32 v[28:29], v[28:29], v[30:31]
	v_mul_f32_e32 v30, 0xbfb8aa3b, v22
	v_mul_f32_e32 v31, 0xbfb8aa3b, v23
	v_exp_f32_e32 v30, v30
	v_exp_f32_e32 v31, v31
	v_add_f32_e32 v30, 1.0, v30
	v_add_f32_e32 v31, 1.0, v31
	v_rcp_f32_e32 v30, v30
	v_rcp_f32_e32 v31, v31
	s_nop 0
	v_pk_mul_f32 v[22:23], v[22:23], v[30:31]
	s_nop 0
	v_pk_mul_f32 v[22:23], v[18:19], v[22:23]
	v_pk_mul_f32 v[18:19], v[24:25], v[132:133] op_sel_hi:[1,0]
	s_nop 0
	v_mul_f32_e32 v24, 0xbfb8aa3b, v18
	v_mul_f32_e32 v25, 0xbfb8aa3b, v19
	v_exp_f32_e32 v24, v24
	v_exp_f32_e32 v25, v25
	v_add_f32_e32 v24, 1.0, v24
	v_add_f32_e32 v25, 1.0, v25
	v_rcp_f32_e32 v24, v24
	v_rcp_f32_e32 v25, v25
	s_nop 0
	v_pk_mul_f32 v[18:19], v[18:19], v[24:25]
	s_nop 0
	v_pk_mul_f32 v[24:25], v[20:21], v[18:19]
	v_cvt_pk_bf16_f32 v20, v22, v23
	v_mad_i64_i32 v[22:23], s[4:5], v176, s9, v[114:115]
	v_cvt_pk_bf16_f32 v18, v26, v27
	v_cvt_pk_bf16_f32 v19, v28, v29
	v_cvt_pk_bf16_f32 v21, v24, v25
	v_lshl_add_u64 v[22:23], v[22:23], 0, v[116:117]
	global_store_dwordx4 v[22:23], v[18:21], off
	s_nop 1
	v_mul_f32_e32 v18, 0xbfb8aa3b, v14
	v_mul_f32_e32 v19, 0xbfb8aa3b, v15
	v_exp_f32_e32 v18, v18
	v_exp_f32_e32 v19, v19
	v_add_f32_e32 v18, 1.0, v18
	v_add_f32_e32 v19, 1.0, v19
	v_rcp_f32_e32 v18, v18
	v_rcp_f32_e32 v19, v19
	s_nop 0
	v_pk_mul_f32 v[14:15], v[14:15], v[18:19]
	s_nop 0
	v_pk_mul_f32 v[10:11], v[10:11], v[14:15]
	v_pk_mul_f32 v[14:15], v[16:17], v[130:131] op_sel_hi:[1,0]
	s_nop 0
	v_mul_f32_e32 v16, 0xbfb8aa3b, v14
	v_mul_f32_e32 v17, 0xbfb8aa3b, v15
	v_exp_f32_e32 v16, v16
	v_exp_f32_e32 v17, v17
	v_add_f32_e32 v16, 1.0, v16
	v_add_f32_e32 v17, 1.0, v17
	v_rcp_f32_e32 v16, v16
	v_rcp_f32_e32 v17, v17
	s_nop 0
	v_pk_mul_f32 v[14:15], v[14:15], v[16:17]
	s_nop 0
	v_pk_mul_f32 v[12:13], v[12:13], v[14:15]
	v_mul_f32_e32 v14, 0xbfb8aa3b, v6
	v_mul_f32_e32 v15, 0xbfb8aa3b, v7
	v_exp_f32_e32 v14, v14
	v_exp_f32_e32 v15, v15
	v_add_f32_e32 v14, 1.0, v14
	v_add_f32_e32 v15, 1.0, v15
	v_rcp_f32_e32 v14, v14
	v_rcp_f32_e32 v15, v15
	s_nop 0
	v_pk_mul_f32 v[6:7], v[6:7], v[14:15]
	s_nop 0
	v_pk_mul_f32 v[6:7], v[2:3], v[6:7]
	v_pk_mul_f32 v[2:3], v[8:9], v[130:131] op_sel_hi:[1,0]
	s_nop 0
	v_mul_f32_e32 v8, 0xbfb8aa3b, v2
	v_mul_f32_e32 v9, 0xbfb8aa3b, v3
	v_exp_f32_e32 v8, v8
	v_exp_f32_e32 v9, v9
	v_add_f32_e32 v8, 1.0, v8
	v_add_f32_e32 v9, 1.0, v9
	v_rcp_f32_e32 v8, v8
	v_rcp_f32_e32 v9, v9
	s_nop 0
	v_pk_mul_f32 v[2:3], v[2:3], v[8:9]
	s_nop 0
	v_pk_mul_f32 v[8:9], v[4:5], v[2:3]
	v_cvt_pk_bf16_f32 v4, v6, v7
	v_mad_i64_i32 v[6:7], s[4:5], v174, s9, v[114:115]
	v_cvt_pk_bf16_f32 v2, v10, v11
	v_cvt_pk_bf16_f32 v3, v12, v13
	v_cvt_pk_bf16_f32 v5, v8, v9
	v_lshl_add_u64 v[6:7], v[6:7], 0, v[116:117]
	s_mov_b64 s[4:5], -1
	global_store_dwordx4 v[6:7], v[2:5], off
	s_cbranch_vccnz .LBB0_1438
	s_branch .LBB0_1437
